# second gate-up GEMM phase now hosts W_DN1 conversion in its idle half round; phase 0 converts only 1792 tiles
# speedup vs baseline: 1.0534x; 1.0100x over previous
.LBB0_935:
	v_readlane_b32 s0, v254, 0
	s_load_dword s50, s[74:75], 0x0
	v_readlane_b32 s6, v255, 30
	s_mov_b32 s30, s6
	v_readlane_b32 s7, v255, 31
	s_waitcnt lgkmcnt(0)
	s_cmpk_eq_i32 s50, 0x100
	s_cselect_b64 s[4:5], -1, 0
	s_cmp_lg_u32 s6, 0
	s_cbranch_scc0 .LBB0_987
	s_cmp_eq_u32 s30, 1
	s_cselect_b64 s[6:7], -1, 0
	s_cmp_gt_i32 s0, 31
	s_cselect_b64 s[8:9], -1, 0
	s_and_b64 s[6:7], s[6:7], s[8:9]
	s_and_b64 s[6:7], s[6:7], s[4:5]
	s_andn2_b64 vcc, exec, s[6:7]
	s_mov_b64 s[6:7], -1
	s_cbranch_vccz .LBB0_943
	s_cmp_eq_u32 s30, 8
	s_cselect_b64 s[6:7], -1, 0
	s_cmp_eq_u32 s30, 16
	s_cselect_b64 s[98:99], -1, 0
	s_or_b64 s[6:7], s[6:7], s[98:99]
	s_and_b64 s[6:7], s[6:7], s[4:5]
	s_cmpk_gt_i32 s0, 0x7f
	s_cselect_b64 s[8:9], -1, 0
	s_and_b64 s[6:7], s[8:9], s[6:7]
	s_andn2_b64 vcc, exec, s[6:7]
	s_mov_b64 s[6:7], -1
	s_cbranch_vccz .LBB0_940
	s_cmp_eq_u32 s30, 11
	s_cselect_b64 s[6:7], -1, 0
	s_and_b64 s[6:7], s[6:7], s[4:5]
	s_and_b64 s[6:7], s[8:9], s[6:7]
	s_andn2_b64 vcc, exec, s[6:7]
	s_mov_b32 s10, 1
	s_cbranch_vccnz .LBB0_989
	s_add_i32 s17, s0, 0x1260
	s_movk_i32 s10, 0x80
	s_movk_i32 s11, 0x17e0
	s_mov_b64 s[6:7], 0

.LBB0_941:
	s_add_i32 s17, s0, 0xe60
	s_movk_i32 s10, 0x80
	s_movk_i32 s11, 0x12e0
	s_cmp_eq_u32 s30, 16
	s_cbranch_scc0 .Lconv16_skip
	s_add_i32 s17, s0, 0x1760
	s_movk_i32 s11, 0x1aa0
.Lconv16_skip:
.LBB0_942:
	s_mov_b64 s[6:7], 0
.LBB0_943:
	s_andn2_b64 vcc, exec, s[6:7]
	s_cbranch_vccnz .LBB0_945
	s_add_i32 s17, s0, 0x6e0
	s_movk_i32 s10, 0xe0
	s_movk_i32 s11, 0xee0

.LBB0_946:
	s_and_b64 s[4:5], s[4:5], exec
	s_movk_i32 s1, 0x700
	s_cselect_b32 s11, s1, 0x1aa0
	s_mov_b32 s17, s0
	s_mov_b32 s10, s50
